# first grid barrier: the 16 per-XCC census counter loads are issued together and waited once instead of 15 dependent round trips
# speedup vs baseline: 1.0037x; 1.0037x over previous
; __device__ __forceinline__ unsigned xb_ld(unsigned* p)              { return __hip_atomic_load(p, __ATOMIC_RELAXED, __HIP_MEMORY_SCOPE_AGENT); }
; __device__ __forceinline__ void xcd_barrier_complete(unsigned* bar, unsigned x, unsigned& nloc, unsigned& nx) {
;     ...
;     for (;;) {
;         sum = 0u; cnt = 0u; mine = 0u;
; #pragma unroll
;         for (unsigned j = 0; j < 16; ++j) { const unsigned c = xb_ld(&bar[XB_XCNT(j)]); sum += c; cnt += (c > 0u) ? 1u : 0u; mine = (j == x) ? c : mine; }
;         if (sum == G) break;
;         __builtin_amdgcn_s_sleep(1);
;         if ((++sp & 255u) == 0u) { if (xb_ld(&bar[XB_TMO])) break; if (sp > XB_SPIN_CAP) { atomicAdd(&bar[XB_TMO], 1u); break; } }
;     }
.LBB0_950:
	s_mov_b64 s[10:11], -1
	s_mov_b64 s[12:13], -1
	s_waitcnt lgkmcnt(0)
	v_readlane_b32 s2, v253, 22
	v_readlane_b32 s3, v253, 23
	s_nop 4
	global_load_dword v0, v113, s[2:3] sc1
	v_readlane_b32 s2, v253, 24
	v_readlane_b32 s3, v253, 25
	s_nop 4
	global_load_dword v1, v113, s[2:3] sc1
	v_readlane_b32 s2, v253, 26
	v_readlane_b32 s3, v253, 27
	s_nop 4
	global_load_dword v2, v113, s[2:3] sc1
	v_readlane_b32 s2, v253, 28
	v_readlane_b32 s3, v253, 29
	s_nop 4
	global_load_dword v3, v113, s[2:3] sc1
	v_readlane_b32 s2, v253, 30
	v_readlane_b32 s3, v253, 31
	s_nop 4
	global_load_dword v4, v113, s[2:3] sc1
	v_readlane_b32 s2, v253, 32
	v_readlane_b32 s3, v253, 33
	s_nop 4
	global_load_dword v5, v113, s[2:3] sc1
	v_readlane_b32 s2, v253, 34
	v_readlane_b32 s3, v253, 35
	s_nop 4
	global_load_dword v6, v113, s[2:3] sc1
	v_readlane_b32 s2, v253, 36
	v_readlane_b32 s3, v253, 37
	s_nop 4
	global_load_dword v7, v113, s[2:3] sc1
	v_readlane_b32 s2, v253, 38
	v_readlane_b32 s3, v253, 39
	s_nop 4
	global_load_dword v8, v113, s[2:3] sc1
	v_readlane_b32 s2, v253, 40
	v_readlane_b32 s3, v253, 41
	s_nop 4
	global_load_dword v9, v113, s[2:3] sc1
	v_readlane_b32 s2, v253, 42
	v_readlane_b32 s3, v253, 43
	s_nop 4
	global_load_dword v10, v113, s[2:3] sc1
	v_readlane_b32 s2, v253, 44
	v_readlane_b32 s3, v253, 45
	s_nop 4
	global_load_dword v11, v113, s[2:3] sc1
	v_readlane_b32 s2, v253, 46
	v_readlane_b32 s3, v253, 47
	s_nop 4
	global_load_dword v12, v113, s[2:3] sc1
	v_readlane_b32 s2, v253, 48
	v_readlane_b32 s3, v253, 49
	s_nop 4
	global_load_dword v13, v113, s[2:3] sc1
	v_readlane_b32 s2, v253, 50
	v_readlane_b32 s3, v253, 51
	s_nop 4
	global_load_dword v14, v113, s[2:3] sc1
	v_readlane_b32 s2, v253, 52
	v_readlane_b32 s3, v253, 53
	s_nop 4
	global_load_dword v15, v113, s[2:3] sc1
	s_waitcnt vmcnt(0)
	v_add_u32_e32 v16, v1, v0
	v_add_u32_e32 v16, v16, v2
	v_add_u32_e32 v16, v16, v3
	v_add_u32_e32 v16, v16, v4
	v_add_u32_e32 v16, v16, v5
	v_add_u32_e32 v16, v16, v6
	v_add_u32_e32 v16, v16, v7
	v_add_u32_e32 v16, v16, v8
	v_add_u32_e32 v16, v16, v9
	v_add_u32_e32 v16, v16, v10
	v_add_u32_e32 v16, v16, v11
	v_add_u32_e32 v16, v16, v12
	v_add_u32_e32 v16, v16, v13
	v_add_u32_e32 v16, v16, v14
	v_add_u32_e32 v16, v16, v15
	v_cmp_eq_u32_e32 vcc, s82, v16
	s_cbranch_vccnz .LBB0_949
	s_and_b32 s1, s0, 0xff
	s_cmp_eq_u32 s1, 0
	s_mov_b64 s[14:15], -1
	s_sleep 1
	s_cbranch_scc1 .LBB0_954
	s_and_b64 vcc, exec, s[14:15]
	s_cbranch_vccz .LBB0_949
